# P2 (x + 0.5 H Wd) epilogue rewritten by hand: residual loads batched 4 row-groups deep with counted vmcnt instead of 8 serialized load-store round trips
# speedup vs baseline: 1.0201x; 1.0023x over previous
;     __device__ __forceinline__ void operator()(const f32x4 (&acc)[2][2][4][2], const Unit& u, int wr, int wc, int fr, int fq) const {
;     ...
;                     const size_t off = (size_t)(u.pm * BM + ai * HALF + wr * 64 + (2 * mh + m2) * 16 + fr) * 1024 + col0 + bj * HALF;
;                     if (!basef) bh[m2][bj] = *(const u32x4*)(xin + off);
;                 }
; #pragma unroll
;             for (int m2 = 0; m2 < 2; ++m2) {
;                 const int m = 2 * mh + m2;
;                 const int row = u.pm * BM + ai * HALF + wr * 64 + m * 16 + fr; float sq = 0.f;
;                 if (basef) {
; #pragma unroll
;                     for (int bj = 0; bj < 2; ++bj) { const size_t off = (size_t)row * 1024 + col0 + bj * HALF; bf[m2][bj][0] = *(const f32x4*)(basef + off); bf[m2][bj][1] = *(const f32x4*)(basef + off + 4); }
;                 }
; #pragma unroll
;                 for (int bj = 0; bj < 2; ++bj) {
;                     const size_t off = (size_t)row * 1024 + col0 + bj * HALF;
;                     float bv[8];
;                     if (basef) { const f32x4 b0 = bf[m2][bj][0], b1 = bf[m2][bj][1]; bv[0] = b0[0]; bv[1] = b0[1]; bv[2] = b0[2]; bv[3] = b0[3]; bv[4] = b1[0]; bv[5] = b1[1]; bv[6] = b1[2]; bv[7] = b1[3]; }
;                     else { const u32x4 gw = bh[m2][bj];
;                         bv[0] = __uint_as_float(gw.x << 16); bv[1] = __uint_as_float(gw.x & 0xffff0000u); bv[2] = __uint_as_float(gw.y << 16); bv[3] = __uint_as_float(gw.y & 0xffff0000u);
;                         bv[4] = __uint_as_float(gw.z << 16); bv[5] = __uint_as_float(gw.z & 0xffff0000u); bv[6] = __uint_as_float(gw.w << 16); bv[7] = __uint_as_float(gw.w & 0xffff0000u); }
;                     float y[8];
; #pragma unroll
;                     for (int e = 0; e < 4; ++e) { y[e] = bv[e] + alpha * acc[ai][bj][m][0][e]; y[4 + e] = bv[4 + e] + alpha * acc[ai][bj][m][1][e]; }
;                     u32x4 w; w.x = cvt_pk_bf16(y[0], y[1]); w.y = cvt_pk_bf16(y[2], y[3]); w.z = cvt_pk_bf16(y[4], y[5]); w.w = cvt_pk_bf16(y[6], y[7]);
;                     *(u32x4*)(xs + off) = w;
;                     if (ss) sq += ((y[0] * y[0] + y[1] * y[1]) + (y[2] * y[2] + y[3] * y[3])) + ((y[4] * y[4] + y[5] * y[5]) + (y[6] * y[6] + y[7] * y[7]));
;                 }
.LBB0_1461:
	v_readlane_b32 s70, v253, 17
	v_readlane_b32 s71, v253, 18
	v_readlane_b32 s50, v253, 13
	v_readlane_b32 s51, v253, 14
	s_mov_b32 s99, 0
	v_lshl_or_b32 v246, s67, 8, v200
	v_lshl_add_u32 v247, s68, 8, v196
	v_mov_b32_e32 v235, 0
	v_lshlrev_b32_e32 v234, 2, v246
	v_lshl_add_u32 v234, v247, 12, v234
	v_lshl_add_u64 v[234:235], s[4:5], 0, v[234:235]
	s_mov_b32 s98, 0x0
	v_lshl_add_u64 v[240:241], v[234:235], 0, s[98:99]
	global_load_dwordx4 v[0:3], v[240:241], off
	global_load_dwordx4 v[4:7], v[240:241], off offset:16
	global_load_dwordx4 v[8:11], v[240:241], off offset:512
	global_load_dwordx4 v[12:15], v[240:241], off offset:528
	s_mov_b32 s98, 0x10000
	v_lshl_add_u64 v[240:241], v[234:235], 0, s[98:99]
	global_load_dwordx4 v[16:19], v[240:241], off
	global_load_dwordx4 v[20:23], v[240:241], off offset:16
	global_load_dwordx4 v[104:107], v[240:241], off offset:512
	global_load_dwordx4 v[116:119], v[240:241], off offset:528
	s_mov_b32 s98, 0x20000
	v_lshl_add_u64 v[240:241], v[234:235], 0, s[98:99]
	global_load_dwordx4 v[184:187], v[240:241], off
	global_load_dwordx4 v[188:191], v[240:241], off offset:16
	global_load_dwordx4 v[192:195], v[240:241], off offset:512
	global_load_dwordx4 v[206:209], v[240:241], off offset:528
	s_mov_b32 s98, 0x30000
	v_lshl_add_u64 v[240:241], v[234:235], 0, s[98:99]
	global_load_dwordx4 v[210:213], v[240:241], off
	global_load_dwordx4 v[214:217], v[240:241], off offset:16
	global_load_dwordx4 v[132:135], v[240:241], off offset:512
	global_load_dwordx4 v[124:127], v[240:241], off offset:528
	v_mov_b32_e32 v237, 0
	v_lshlrev_b32_e32 v236, 1, v246
	v_lshl_add_u32 v236, v247, 11, v236
	v_lshl_add_u64 v[236:237], s[50:51], 0, v[236:237]
	v_bfe_u32 v238, v198, 6, 2
	v_lshlrev_b32_e32 v238, 2, v238
	v_lshl_add_u32 v238, s67, 4, v238
	v_mov_b32_e32 v239, 0
	v_lshl_add_u32 v238, v247, 6, v238
	v_lshl_add_u64 v[238:239], s[0:1], 0, v[238:239]
	v_xor_b32_e32 v242, 16, v204
	v_xor_b32_e32 v243, 32, v204
	v_lshlrev_b32_e32 v242, 2, v242
	v_lshlrev_b32_e32 v243, 2, v243
	s_waitcnt vmcnt(12)
	v_fmac_f32_e32 v0, 0.5, v28
	v_fmac_f32_e32 v1, 0.5, v29
	v_fmac_f32_e32 v2, 0.5, v30
	v_fmac_f32_e32 v3, 0.5, v31
	v_fmac_f32_e32 v4, 0.5, v24
	v_fmac_f32_e32 v5, 0.5, v25
	v_fmac_f32_e32 v6, 0.5, v26
	v_fmac_f32_e32 v7, 0.5, v27
	v_fmac_f32_e32 v8, 0.5, v36
	v_fmac_f32_e32 v9, 0.5, v37
	v_fmac_f32_e32 v10, 0.5, v38
	v_fmac_f32_e32 v11, 0.5, v39
	v_fmac_f32_e32 v12, 0.5, v32
	v_fmac_f32_e32 v13, 0.5, v33
	v_fmac_f32_e32 v14, 0.5, v34
	v_fmac_f32_e32 v15, 0.5, v35
	v_mul_f32_e32 v24, v0, v0
	v_mul_f32_e32 v25, v2, v2
	v_mul_f32_e32 v26, v4, v4
	v_mul_f32_e32 v27, v6, v6
	v_fmac_f32_e32 v24, v1, v1
	v_fmac_f32_e32 v25, v3, v3
	v_fmac_f32_e32 v26, v5, v5
	v_fmac_f32_e32 v27, v7, v7
	v_add_f32_e32 v24, v24, v25
	v_add_f32_e32 v26, v26, v27
	v_add_f32_e32 v24, v24, v26
	v_mul_f32_e32 v32, v8, v8
	v_mul_f32_e32 v33, v10, v10
	v_mul_f32_e32 v34, v12, v12
	v_mul_f32_e32 v35, v14, v14
	v_fmac_f32_e32 v32, v9, v9
	v_fmac_f32_e32 v33, v11, v11
	v_fmac_f32_e32 v34, v13, v13
	v_fmac_f32_e32 v35, v15, v15
	v_add_f32_e32 v32, v32, v33
	v_add_f32_e32 v34, v34, v35
	v_add_f32_e32 v32, v32, v34
	v_add_f32_e32 v244, v24, v32
	ds_bpermute_b32 v245, v242, v244
	s_mov_b32 s98, 0x0
	v_lshl_add_u64 v[240:241], v[236:237], 0, s[98:99]
	v_cvt_pk_bf16_f32 v28, v0, v1
	v_cvt_pk_bf16_f32 v29, v2, v3
	v_cvt_pk_bf16_f32 v30, v4, v5
	v_cvt_pk_bf16_f32 v31, v6, v7
	global_store_dwordx4 v[240:241], v[28:31], off
	v_cvt_pk_bf16_f32 v36, v8, v9
	v_cvt_pk_bf16_f32 v37, v10, v11
	v_cvt_pk_bf16_f32 v38, v12, v13
	v_cvt_pk_bf16_f32 v39, v14, v15
	global_store_dwordx4 v[240:241], v[36:39], off offset:256
	s_waitcnt lgkmcnt(0)
	v_add_f32_e32 v244, v244, v245
	ds_bpermute_b32 v245, v243, v244
	s_mov_b32 s98, 0x0
	v_lshl_add_u64 v[240:241], v[238:239], 0, s[98:99]
	s_waitcnt lgkmcnt(0)
	v_add_f32_e32 v244, v244, v245
	s_and_saveexec_b64 s[50:51], s[8:9]
	global_store_dword v[240:241], v244, off
	s_mov_b64 exec, s[50:51]
	s_mov_b32 s98, 0x80000
	v_lshl_add_u64 v[240:241], v[234:235], 0, s[98:99]
	global_load_dwordx4 v[0:3], v[240:241], off
	global_load_dwordx4 v[4:7], v[240:241], off offset:16
	global_load_dwordx4 v[8:11], v[240:241], off offset:512
	global_load_dwordx4 v[12:15], v[240:241], off offset:528
	s_waitcnt vmcnt(15)
	v_fmac_f32_e32 v16, 0.5, v44
	v_fmac_f32_e32 v17, 0.5, v45
	v_fmac_f32_e32 v18, 0.5, v46
	v_fmac_f32_e32 v19, 0.5, v47
	v_fmac_f32_e32 v20, 0.5, v40
	v_fmac_f32_e32 v21, 0.5, v41
	v_fmac_f32_e32 v22, 0.5, v42
	v_fmac_f32_e32 v23, 0.5, v43
	v_fmac_f32_e32 v104, 0.5, v164
	v_fmac_f32_e32 v105, 0.5, v165
	v_fmac_f32_e32 v106, 0.5, v166
	v_fmac_f32_e32 v107, 0.5, v167
	v_fmac_f32_e32 v116, 0.5, v160
	v_fmac_f32_e32 v117, 0.5, v161
	v_fmac_f32_e32 v118, 0.5, v162
	v_fmac_f32_e32 v119, 0.5, v163
	v_mul_f32_e32 v40, v16, v16
	v_mul_f32_e32 v41, v18, v18
	v_mul_f32_e32 v42, v20, v20
	v_mul_f32_e32 v43, v22, v22
	v_fmac_f32_e32 v40, v17, v17
	v_fmac_f32_e32 v41, v19, v19
	v_fmac_f32_e32 v42, v21, v21
	v_fmac_f32_e32 v43, v23, v23
	v_add_f32_e32 v40, v40, v41
	v_add_f32_e32 v42, v42, v43
	v_add_f32_e32 v40, v40, v42
	v_mul_f32_e32 v160, v104, v104
	v_mul_f32_e32 v161, v106, v106
	v_mul_f32_e32 v162, v116, v116
	v_mul_f32_e32 v163, v118, v118
	v_fmac_f32_e32 v160, v105, v105
	v_fmac_f32_e32 v161, v107, v107
	v_fmac_f32_e32 v162, v117, v117
	v_fmac_f32_e32 v163, v119, v119
	v_add_f32_e32 v160, v160, v161
	v_add_f32_e32 v162, v162, v163
	v_add_f32_e32 v160, v160, v162
	v_add_f32_e32 v244, v40, v160
	ds_bpermute_b32 v245, v242, v244
	s_mov_b32 s98, 0x8000
	v_lshl_add_u64 v[240:241], v[236:237], 0, s[98:99]
	v_cvt_pk_bf16_f32 v44, v16, v17
	v_cvt_pk_bf16_f32 v45, v18, v19
	v_cvt_pk_bf16_f32 v46, v20, v21
	v_cvt_pk_bf16_f32 v47, v22, v23
	global_store_dwordx4 v[240:241], v[44:47], off
	v_cvt_pk_bf16_f32 v164, v104, v105
	v_cvt_pk_bf16_f32 v165, v106, v107
	v_cvt_pk_bf16_f32 v166, v116, v117
	v_cvt_pk_bf16_f32 v167, v118, v119
	global_store_dwordx4 v[240:241], v[164:167], off offset:256
	s_waitcnt lgkmcnt(0)
;     __device__ __forceinline__ void operator()(const f32x4 (&acc)[2][2][4][2], const Unit& u, int wr, int wc, int fr, int fq) const {
;     ...
;                     const size_t off = (size_t)(u.pm * BM + ai * HALF + wr * 64 + (2 * mh + m2) * 16 + fr) * 1024 + col0 + bj * HALF;
;                     if (!basef) bh[m2][bj] = *(const u32x4*)(xin + off);
;                 }
; #pragma unroll
;             for (int m2 = 0; m2 < 2; ++m2) {
;                 const int m = 2 * mh + m2;
;                 const int row = u.pm * BM + ai * HALF + wr * 64 + m * 16 + fr; float sq = 0.f;
;                 if (basef) {
; #pragma unroll
;                     for (int bj = 0; bj < 2; ++bj) { const size_t off = (size_t)row * 1024 + col0 + bj * HALF; bf[m2][bj][0] = *(const f32x4*)(basef + off); bf[m2][bj][1] = *(const f32x4*)(basef + off + 4); }
;                 }
; #pragma unroll
;                 for (int bj = 0; bj < 2; ++bj) {
;                     const size_t off = (size_t)row * 1024 + col0 + bj * HALF;
;                     float bv[8];
;                     if (basef) { const f32x4 b0 = bf[m2][bj][0], b1 = bf[m2][bj][1]; bv[0] = b0[0]; bv[1] = b0[1]; bv[2] = b0[2]; bv[3] = b0[3]; bv[4] = b1[0]; bv[5] = b1[1]; bv[6] = b1[2]; bv[7] = b1[3]; }
;                     else { const u32x4 gw = bh[m2][bj];
;                         bv[0] = __uint_as_float(gw.x << 16); bv[1] = __uint_as_float(gw.x & 0xffff0000u); bv[2] = __uint_as_float(gw.y << 16); bv[3] = __uint_as_float(gw.y & 0xffff0000u);
;                         bv[4] = __uint_as_float(gw.z << 16); bv[5] = __uint_as_float(gw.z & 0xffff0000u); bv[6] = __uint_as_float(gw.w << 16); bv[7] = __uint_as_float(gw.w & 0xffff0000u); }
;                     float y[8];
; #pragma unroll
;                     for (int e = 0; e < 4; ++e) { y[e] = bv[e] + alpha * acc[ai][bj][m][0][e]; y[4 + e] = bv[4 + e] + alpha * acc[ai][bj][m][1][e]; }
;                     u32x4 w; w.x = cvt_pk_bf16(y[0], y[1]); w.y = cvt_pk_bf16(y[2], y[3]); w.z = cvt_pk_bf16(y[4], y[5]); w.w = cvt_pk_bf16(y[6], y[7]);
;                     *(u32x4*)(xs + off) = w;
;                     if (ss) sq += ((y[0] * y[0] + y[1] * y[1]) + (y[2] * y[2] + y[3] * y[3])) + ((y[4] * y[4] + y[5] * y[5]) + (y[6] * y[6] + y[7] * y[7]));
;                 }
	v_add_f32_e32 v244, v244, v245
	ds_bpermute_b32 v245, v243, v244
	s_mov_b32 s98, 0x400
	v_lshl_add_u64 v[240:241], v[238:239], 0, s[98:99]
	s_waitcnt lgkmcnt(0)
	v_add_f32_e32 v244, v244, v245
	s_and_saveexec_b64 s[50:51], s[8:9]
	global_store_dword v[240:241], v244, off
	s_mov_b64 exec, s[50:51]
	s_mov_b32 s98, 0x90000
	v_lshl_add_u64 v[240:241], v[234:235], 0, s[98:99]
	global_load_dwordx4 v[16:19], v[240:241], off
	global_load_dwordx4 v[20:23], v[240:241], off offset:16
	global_load_dwordx4 v[104:107], v[240:241], off offset:512
	global_load_dwordx4 v[116:119], v[240:241], off offset:528
	s_waitcnt vmcnt(18)
	v_fmac_f32_e32 v184, 0.5, v156
	v_fmac_f32_e32 v185, 0.5, v157
	v_fmac_f32_e32 v186, 0.5, v158
	v_fmac_f32_e32 v187, 0.5, v159
	v_fmac_f32_e32 v188, 0.5, v152
	v_fmac_f32_e32 v189, 0.5, v153
	v_fmac_f32_e32 v190, 0.5, v154
	v_fmac_f32_e32 v191, 0.5, v155
	v_fmac_f32_e32 v192, 0.5, v148
	v_fmac_f32_e32 v193, 0.5, v149
	v_fmac_f32_e32 v194, 0.5, v150
	v_fmac_f32_e32 v195, 0.5, v151
	v_fmac_f32_e32 v206, 0.5, v144
	v_fmac_f32_e32 v207, 0.5, v145
	v_fmac_f32_e32 v208, 0.5, v146
	v_fmac_f32_e32 v209, 0.5, v147
	v_mul_f32_e32 v152, v184, v184
	v_mul_f32_e32 v153, v186, v186
	v_mul_f32_e32 v154, v188, v188
	v_mul_f32_e32 v155, v190, v190
	v_fmac_f32_e32 v152, v185, v185
	v_fmac_f32_e32 v153, v187, v187
	v_fmac_f32_e32 v154, v189, v189
	v_fmac_f32_e32 v155, v191, v191
	v_add_f32_e32 v152, v152, v153
	v_add_f32_e32 v154, v154, v155
	v_add_f32_e32 v152, v152, v154
	v_mul_f32_e32 v144, v192, v192
	v_mul_f32_e32 v145, v194, v194
	v_mul_f32_e32 v146, v206, v206
	v_mul_f32_e32 v147, v208, v208
	v_fmac_f32_e32 v144, v193, v193
	v_fmac_f32_e32 v145, v195, v195
	v_fmac_f32_e32 v146, v207, v207
	v_fmac_f32_e32 v147, v209, v209
	v_add_f32_e32 v144, v144, v145
	v_add_f32_e32 v146, v146, v147
	v_add_f32_e32 v144, v144, v146
	v_add_f32_e32 v244, v152, v144
	ds_bpermute_b32 v245, v242, v244
	s_mov_b32 s98, 0x10000
	v_lshl_add_u64 v[240:241], v[236:237], 0, s[98:99]
	v_cvt_pk_bf16_f32 v156, v184, v185
	v_cvt_pk_bf16_f32 v157, v186, v187
	v_cvt_pk_bf16_f32 v158, v188, v189
	v_cvt_pk_bf16_f32 v159, v190, v191
	global_store_dwordx4 v[240:241], v[156:159], off
	v_cvt_pk_bf16_f32 v148, v192, v193
	v_cvt_pk_bf16_f32 v149, v194, v195
	v_cvt_pk_bf16_f32 v150, v206, v207
	v_cvt_pk_bf16_f32 v151, v208, v209
	global_store_dwordx4 v[240:241], v[148:151], off offset:256
	s_waitcnt lgkmcnt(0)
	v_add_f32_e32 v244, v244, v245
	ds_bpermute_b32 v245, v243, v244
	s_mov_b32 s98, 0x800
	v_lshl_add_u64 v[240:241], v[238:239], 0, s[98:99]
	s_waitcnt lgkmcnt(0)
	v_add_f32_e32 v244, v244, v245
	s_and_saveexec_b64 s[50:51], s[8:9]
	global_store_dword v[240:241], v244, off
	s_mov_b64 exec, s[50:51]
	s_mov_b32 s98, 0xa0000
	v_lshl_add_u64 v[240:241], v[234:235], 0, s[98:99]
	global_load_dwordx4 v[184:187], v[240:241], off
	global_load_dwordx4 v[188:191], v[240:241], off offset:16
	global_load_dwordx4 v[192:195], v[240:241], off offset:512
	global_load_dwordx4 v[206:209], v[240:241], off offset:528
	s_waitcnt vmcnt(21)
	v_fmac_f32_e32 v210, 0.5, v140
	v_fmac_f32_e32 v211, 0.5, v141
	v_fmac_f32_e32 v212, 0.5, v142
	v_fmac_f32_e32 v213, 0.5, v143
	v_fmac_f32_e32 v214, 0.5, v136
	v_fmac_f32_e32 v215, 0.5, v137
	v_fmac_f32_e32 v216, 0.5, v138
	v_fmac_f32_e32 v217, 0.5, v139
	v_fmac_f32_e32 v132, 0.5, v128
	v_fmac_f32_e32 v133, 0.5, v129
	v_fmac_f32_e32 v134, 0.5, v130
	v_fmac_f32_e32 v135, 0.5, v131
	v_fmac_f32_e32 v124, 0.5, v120
	v_fmac_f32_e32 v125, 0.5, v121
	v_fmac_f32_e32 v126, 0.5, v122
	v_fmac_f32_e32 v127, 0.5, v123
	v_mul_f32_e32 v136, v210, v210
	v_mul_f32_e32 v137, v212, v212
	v_mul_f32_e32 v138, v214, v214
	v_mul_f32_e32 v139, v216, v216
	v_fmac_f32_e32 v136, v211, v211
	v_fmac_f32_e32 v137, v213, v213
	v_fmac_f32_e32 v138, v215, v215
	v_fmac_f32_e32 v139, v217, v217
	v_add_f32_e32 v136, v136, v137
	v_add_f32_e32 v138, v138, v139
	v_add_f32_e32 v136, v136, v138
	v_mul_f32_e32 v120, v132, v132
	v_mul_f32_e32 v121, v134, v134
	v_mul_f32_e32 v122, v124, v124
	v_mul_f32_e32 v123, v126, v126
	v_fmac_f32_e32 v120, v133, v133
	v_fmac_f32_e32 v121, v135, v135
	v_fmac_f32_e32 v122, v125, v125
	v_fmac_f32_e32 v123, v127, v127
	v_add_f32_e32 v120, v120, v121
	v_add_f32_e32 v122, v122, v123
	v_add_f32_e32 v120, v120, v122
	v_add_f32_e32 v244, v136, v120
	ds_bpermute_b32 v245, v242, v244
	s_mov_b32 s98, 0x18000
	v_lshl_add_u64 v[240:241], v[236:237], 0, s[98:99]
	v_cvt_pk_bf16_f32 v140, v210, v211
	v_cvt_pk_bf16_f32 v141, v212, v213
	v_cvt_pk_bf16_f32 v142, v214, v215
	v_cvt_pk_bf16_f32 v143, v216, v217
	global_store_dwordx4 v[240:241], v[140:143], off
	v_cvt_pk_bf16_f32 v128, v132, v133
	v_cvt_pk_bf16_f32 v129, v134, v135
	v_cvt_pk_bf16_f32 v130, v124, v125
	v_cvt_pk_bf16_f32 v131, v126, v127
	global_store_dwordx4 v[240:241], v[128:131], off offset:256
	s_waitcnt lgkmcnt(0)
	v_add_f32_e32 v244, v244, v245
	ds_bpermute_b32 v245, v243, v244
	s_mov_b32 s98, 0xc00
	v_lshl_add_u64 v[240:241], v[238:239], 0, s[98:99]
	s_waitcnt lgkmcnt(0)
	v_add_f32_e32 v244, v244, v245
	s_and_saveexec_b64 s[50:51], s[8:9]
	global_store_dword v[240:241], v244, off
	s_mov_b64 exec, s[50:51]
	s_mov_b32 s98, 0xb0000
	v_lshl_add_u64 v[240:241], v[234:235], 0, s[98:99]
	global_load_dwordx4 v[210:213], v[240:241], off
	global_load_dwordx4 v[214:217], v[240:241], off offset:16
	global_load_dwordx4 v[132:135], v[240:241], off offset:512
	global_load_dwordx4 v[124:127], v[240:241], off offset:528
	s_waitcnt vmcnt(21)
; __device__ __forceinline__ unsigned cvt_pk_bf16(float lo, float hi) { unsigned r; asm volatile("v_cvt_pk_bf16_f32 %0, %1, %2" : "=v"(r) : "v"(lo), "v"(hi)); return r; }
;     __device__ __forceinline__ void operator()(const f32x4 (&acc)[2][2][4][2], const Unit& u, int wr, int wc, int fr, int fq) const {
;     ...
;                     for (int bj = 0; bj < 2; ++bj) { const size_t off = (size_t)row * 1024 + col0 + bj * HALF; bf[m2][bj][0] = *(const f32x4*)(basef + off); bf[m2][bj][1] = *(const f32x4*)(basef + off + 4); }
;                 }
; #pragma unroll
;                 for (int bj = 0; bj < 2; ++bj) {
;                     const size_t off = (size_t)row * 1024 + col0 + bj * HALF;
;                     float bv[8];
;                     if (basef) { const f32x4 b0 = bf[m2][bj][0], b1 = bf[m2][bj][1]; bv[0] = b0[0]; bv[1] = b0[1]; bv[2] = b0[2]; bv[3] = b0[3]; bv[4] = b1[0]; bv[5] = b1[1]; bv[6] = b1[2]; bv[7] = b1[3]; }
;                     else { const u32x4 gw = bh[m2][bj];
;                         bv[0] = __uint_as_float(gw.x << 16); bv[1] = __uint_as_float(gw.x & 0xffff0000u); bv[2] = __uint_as_float(gw.y << 16); bv[3] = __uint_as_float(gw.y & 0xffff0000u);
;                         bv[4] = __uint_as_float(gw.z << 16); bv[5] = __uint_as_float(gw.z & 0xffff0000u); bv[6] = __uint_as_float(gw.w << 16); bv[7] = __uint_as_float(gw.w & 0xffff0000u); }
;                     float y[8];
; #pragma unroll
;                     for (int e = 0; e < 4; ++e) { y[e] = bv[e] + alpha * acc[ai][bj][m][0][e]; y[4 + e] = bv[4 + e] + alpha * acc[ai][bj][m][1][e]; }
;                     u32x4 w; w.x = cvt_pk_bf16(y[0], y[1]); w.y = cvt_pk_bf16(y[2], y[3]); w.z = cvt_pk_bf16(y[4], y[5]); w.w = cvt_pk_bf16(y[6], y[7]);
;                     *(u32x4*)(xs + off) = w;
;                     if (ss) sq += ((y[0] * y[0] + y[1] * y[1]) + (y[2] * y[2] + y[3] * y[3])) + ((y[4] * y[4] + y[5] * y[5]) + (y[6] * y[6] + y[7] * y[7]));
;                 }
;                 if (ss) { sq += __shfl_xor(sq, 16); sq += __shfl_xor(sq, 32); if (fq == 0) ss[(size_t)row * 16 + u.pn * 4 + wc] = sq; }
	v_fmac_f32_e32 v0, 0.5, v112
	v_fmac_f32_e32 v1, 0.5, v113
	v_fmac_f32_e32 v2, 0.5, v114
	v_fmac_f32_e32 v3, 0.5, v115
	v_fmac_f32_e32 v4, 0.5, v108
	v_fmac_f32_e32 v5, 0.5, v109
	v_fmac_f32_e32 v6, 0.5, v110
	v_fmac_f32_e32 v7, 0.5, v111
	v_fmac_f32_e32 v8, 0.5, v100
	v_fmac_f32_e32 v9, 0.5, v101
	v_fmac_f32_e32 v10, 0.5, v102
	v_fmac_f32_e32 v11, 0.5, v103
	v_fmac_f32_e32 v12, 0.5, v96
	v_fmac_f32_e32 v13, 0.5, v97
	v_fmac_f32_e32 v14, 0.5, v98
	v_fmac_f32_e32 v15, 0.5, v99
	v_mul_f32_e32 v108, v0, v0
	v_mul_f32_e32 v109, v2, v2
	v_mul_f32_e32 v110, v4, v4
	v_mul_f32_e32 v111, v6, v6
	v_fmac_f32_e32 v108, v1, v1
	v_fmac_f32_e32 v109, v3, v3
	v_fmac_f32_e32 v110, v5, v5
	v_fmac_f32_e32 v111, v7, v7
	v_add_f32_e32 v108, v108, v109
	v_add_f32_e32 v110, v110, v111
	v_add_f32_e32 v108, v108, v110
	v_mul_f32_e32 v96, v8, v8
	v_mul_f32_e32 v97, v10, v10
	v_mul_f32_e32 v98, v12, v12
	v_mul_f32_e32 v99, v14, v14
	v_fmac_f32_e32 v96, v9, v9
	v_fmac_f32_e32 v97, v11, v11
	v_fmac_f32_e32 v98, v13, v13
	v_fmac_f32_e32 v99, v15, v15
	v_add_f32_e32 v96, v96, v97
	v_add_f32_e32 v98, v98, v99
	v_add_f32_e32 v96, v96, v98
	v_add_f32_e32 v244, v108, v96
	ds_bpermute_b32 v245, v242, v244
	s_mov_b32 s98, 0x40000
	v_lshl_add_u64 v[240:241], v[236:237], 0, s[98:99]
	v_cvt_pk_bf16_f32 v112, v0, v1
	v_cvt_pk_bf16_f32 v113, v2, v3
	v_cvt_pk_bf16_f32 v114, v4, v5
	v_cvt_pk_bf16_f32 v115, v6, v7
	global_store_dwordx4 v[240:241], v[112:115], off
	v_cvt_pk_bf16_f32 v100, v8, v9
	v_cvt_pk_bf16_f32 v101, v10, v11
	v_cvt_pk_bf16_f32 v102, v12, v13
	v_cvt_pk_bf16_f32 v103, v14, v15
	global_store_dwordx4 v[240:241], v[100:103], off offset:256
	s_waitcnt lgkmcnt(0)
	v_add_f32_e32 v244, v244, v245
	ds_bpermute_b32 v245, v243, v244
	s_mov_b32 s98, 0x2000
	v_lshl_add_u64 v[240:241], v[238:239], 0, s[98:99]
	s_waitcnt lgkmcnt(0)
	v_add_f32_e32 v244, v244, v245
	s_and_saveexec_b64 s[50:51], s[8:9]
	global_store_dword v[240:241], v244, off
	s_mov_b64 exec, s[50:51]
	s_waitcnt vmcnt(17)
	v_fmac_f32_e32 v16, 0.5, v92
	v_fmac_f32_e32 v17, 0.5, v93
	v_fmac_f32_e32 v18, 0.5, v94
	v_fmac_f32_e32 v19, 0.5, v95
	v_fmac_f32_e32 v20, 0.5, v88
	v_fmac_f32_e32 v21, 0.5, v89
	v_fmac_f32_e32 v22, 0.5, v90
	v_fmac_f32_e32 v23, 0.5, v91
	v_fmac_f32_e32 v104, 0.5, v84
	v_fmac_f32_e32 v105, 0.5, v85
	v_fmac_f32_e32 v106, 0.5, v86
	v_fmac_f32_e32 v107, 0.5, v87
	v_fmac_f32_e32 v116, 0.5, v80
	v_fmac_f32_e32 v117, 0.5, v81
	v_fmac_f32_e32 v118, 0.5, v82
	v_fmac_f32_e32 v119, 0.5, v83
	v_mul_f32_e32 v88, v16, v16
	v_mul_f32_e32 v89, v18, v18
	v_mul_f32_e32 v90, v20, v20
	v_mul_f32_e32 v91, v22, v22
	v_fmac_f32_e32 v88, v17, v17
	v_fmac_f32_e32 v89, v19, v19
	v_fmac_f32_e32 v90, v21, v21
	v_fmac_f32_e32 v91, v23, v23
	v_add_f32_e32 v88, v88, v89
	v_add_f32_e32 v90, v90, v91
	v_add_f32_e32 v88, v88, v90
	v_mul_f32_e32 v80, v104, v104
	v_mul_f32_e32 v81, v106, v106
	v_mul_f32_e32 v82, v116, v116
	v_mul_f32_e32 v83, v118, v118
	v_fmac_f32_e32 v80, v105, v105
	v_fmac_f32_e32 v81, v107, v107
	v_fmac_f32_e32 v82, v117, v117
	v_fmac_f32_e32 v83, v119, v119
	v_add_f32_e32 v80, v80, v81
	v_add_f32_e32 v82, v82, v83
	v_add_f32_e32 v80, v80, v82
	v_add_f32_e32 v244, v88, v80
	ds_bpermute_b32 v245, v242, v244
	s_mov_b32 s98, 0x48000
	v_lshl_add_u64 v[240:241], v[236:237], 0, s[98:99]
	v_cvt_pk_bf16_f32 v92, v16, v17
	v_cvt_pk_bf16_f32 v93, v18, v19
	v_cvt_pk_bf16_f32 v94, v20, v21
	v_cvt_pk_bf16_f32 v95, v22, v23
	global_store_dwordx4 v[240:241], v[92:95], off
	v_cvt_pk_bf16_f32 v84, v104, v105
	v_cvt_pk_bf16_f32 v85, v106, v107
	v_cvt_pk_bf16_f32 v86, v116, v117
	v_cvt_pk_bf16_f32 v87, v118, v119
	global_store_dwordx4 v[240:241], v[84:87], off offset:256
	s_waitcnt lgkmcnt(0)
	v_add_f32_e32 v244, v244, v245
	ds_bpermute_b32 v245, v243, v244
	s_mov_b32 s98, 0x2400
	v_lshl_add_u64 v[240:241], v[238:239], 0, s[98:99]
	s_waitcnt lgkmcnt(0)
	v_add_f32_e32 v244, v244, v245
	s_and_saveexec_b64 s[50:51], s[8:9]
	global_store_dword v[240:241], v244, off
	s_mov_b64 exec, s[50:51]
	s_waitcnt vmcnt(13)
; __device__ __forceinline__ unsigned cvt_pk_bf16(float lo, float hi) { unsigned r; asm volatile("v_cvt_pk_bf16_f32 %0, %1, %2" : "=v"(r) : "v"(lo), "v"(hi)); return r; }
;     __device__ __forceinline__ void operator()(const f32x4 (&acc)[2][2][4][2], const Unit& u, int wr, int wc, int fr, int fq) const {
;     ...
;                 for (int bj = 0; bj < 2; ++bj) {
;                     const size_t off = (size_t)row * 1024 + col0 + bj * HALF;
;                     float bv[8];
;                     if (basef) { const f32x4 b0 = bf[m2][bj][0], b1 = bf[m2][bj][1]; bv[0] = b0[0]; bv[1] = b0[1]; bv[2] = b0[2]; bv[3] = b0[3]; bv[4] = b1[0]; bv[5] = b1[1]; bv[6] = b1[2]; bv[7] = b1[3]; }
;                     else { const u32x4 gw = bh[m2][bj];
;                         bv[0] = __uint_as_float(gw.x << 16); bv[1] = __uint_as_float(gw.x & 0xffff0000u); bv[2] = __uint_as_float(gw.y << 16); bv[3] = __uint_as_float(gw.y & 0xffff0000u);
;                         bv[4] = __uint_as_float(gw.z << 16); bv[5] = __uint_as_float(gw.z & 0xffff0000u); bv[6] = __uint_as_float(gw.w << 16); bv[7] = __uint_as_float(gw.w & 0xffff0000u); }
;                     float y[8];
; #pragma unroll
;                     for (int e = 0; e < 4; ++e) { y[e] = bv[e] + alpha * acc[ai][bj][m][0][e]; y[4 + e] = bv[4 + e] + alpha * acc[ai][bj][m][1][e]; }
;                     u32x4 w; w.x = cvt_pk_bf16(y[0], y[1]); w.y = cvt_pk_bf16(y[2], y[3]); w.z = cvt_pk_bf16(y[4], y[5]); w.w = cvt_pk_bf16(y[6], y[7]);
;                     *(u32x4*)(xs + off) = w;
;                     if (ss) sq += ((y[0] * y[0] + y[1] * y[1]) + (y[2] * y[2] + y[3] * y[3])) + ((y[4] * y[4] + y[5] * y[5]) + (y[6] * y[6] + y[7] * y[7]));
;                 }
;                 if (ss) { sq += __shfl_xor(sq, 16); sq += __shfl_xor(sq, 32); if (fq == 0) ss[(size_t)row * 16 + u.pn * 4 + wc] = sq; }
	v_fmac_f32_e32 v184, 0.5, v76
	v_fmac_f32_e32 v185, 0.5, v77
	v_fmac_f32_e32 v186, 0.5, v78
	v_fmac_f32_e32 v187, 0.5, v79
	v_fmac_f32_e32 v188, 0.5, v72
	v_fmac_f32_e32 v189, 0.5, v73
	v_fmac_f32_e32 v190, 0.5, v74
	v_fmac_f32_e32 v191, 0.5, v75
	v_fmac_f32_e32 v192, 0.5, v68
	v_fmac_f32_e32 v193, 0.5, v69
	v_fmac_f32_e32 v194, 0.5, v70
	v_fmac_f32_e32 v195, 0.5, v71
	v_fmac_f32_e32 v206, 0.5, v64
	v_fmac_f32_e32 v207, 0.5, v65
	v_fmac_f32_e32 v208, 0.5, v66
	v_fmac_f32_e32 v209, 0.5, v67
	v_mul_f32_e32 v72, v184, v184
	v_mul_f32_e32 v73, v186, v186
	v_mul_f32_e32 v74, v188, v188
	v_mul_f32_e32 v75, v190, v190
	v_fmac_f32_e32 v72, v185, v185
	v_fmac_f32_e32 v73, v187, v187
	v_fmac_f32_e32 v74, v189, v189
	v_fmac_f32_e32 v75, v191, v191
	v_add_f32_e32 v72, v72, v73
	v_add_f32_e32 v74, v74, v75
	v_add_f32_e32 v72, v72, v74
	v_mul_f32_e32 v64, v192, v192
	v_mul_f32_e32 v65, v194, v194
	v_mul_f32_e32 v66, v206, v206
	v_mul_f32_e32 v67, v208, v208
	v_fmac_f32_e32 v64, v193, v193
	v_fmac_f32_e32 v65, v195, v195
	v_fmac_f32_e32 v66, v207, v207
	v_fmac_f32_e32 v67, v209, v209
	v_add_f32_e32 v64, v64, v65
	v_add_f32_e32 v66, v66, v67
	v_add_f32_e32 v64, v64, v66
	v_add_f32_e32 v244, v72, v64
	ds_bpermute_b32 v245, v242, v244
	s_mov_b32 s98, 0x50000
	v_lshl_add_u64 v[240:241], v[236:237], 0, s[98:99]
	v_cvt_pk_bf16_f32 v76, v184, v185
	v_cvt_pk_bf16_f32 v77, v186, v187
	v_cvt_pk_bf16_f32 v78, v188, v189
	v_cvt_pk_bf16_f32 v79, v190, v191
	global_store_dwordx4 v[240:241], v[76:79], off
	v_cvt_pk_bf16_f32 v68, v192, v193
	v_cvt_pk_bf16_f32 v69, v194, v195
	v_cvt_pk_bf16_f32 v70, v206, v207
	v_cvt_pk_bf16_f32 v71, v208, v209
	global_store_dwordx4 v[240:241], v[68:71], off offset:256
	s_waitcnt lgkmcnt(0)
	v_add_f32_e32 v244, v244, v245
	ds_bpermute_b32 v245, v243, v244
	s_mov_b32 s98, 0x2800
	v_lshl_add_u64 v[240:241], v[238:239], 0, s[98:99]
	s_waitcnt lgkmcnt(0)
	v_add_f32_e32 v244, v244, v245
	s_and_saveexec_b64 s[50:51], s[8:9]
	global_store_dword v[240:241], v244, off
	s_mov_b64 exec, s[50:51]
	s_waitcnt vmcnt(9)
	v_fmac_f32_e32 v210, 0.5, v60
	v_fmac_f32_e32 v211, 0.5, v61
	v_fmac_f32_e32 v212, 0.5, v62
	v_fmac_f32_e32 v213, 0.5, v63
	v_fmac_f32_e32 v214, 0.5, v56
	v_fmac_f32_e32 v215, 0.5, v57
	v_fmac_f32_e32 v216, 0.5, v58
	v_fmac_f32_e32 v217, 0.5, v59
	v_fmac_f32_e32 v132, 0.5, v52
	v_fmac_f32_e32 v133, 0.5, v53
	v_fmac_f32_e32 v134, 0.5, v54
	v_fmac_f32_e32 v135, 0.5, v55
	v_fmac_f32_e32 v124, 0.5, v48
	v_fmac_f32_e32 v125, 0.5, v49
	v_fmac_f32_e32 v126, 0.5, v50
	v_fmac_f32_e32 v127, 0.5, v51
	v_mul_f32_e32 v56, v210, v210
	v_mul_f32_e32 v57, v212, v212
	v_mul_f32_e32 v58, v214, v214
	v_mul_f32_e32 v59, v216, v216
	v_fmac_f32_e32 v56, v211, v211
	v_fmac_f32_e32 v57, v213, v213
	v_fmac_f32_e32 v58, v215, v215
	v_fmac_f32_e32 v59, v217, v217
	v_add_f32_e32 v56, v56, v57
	v_add_f32_e32 v58, v58, v59
	v_add_f32_e32 v56, v56, v58
	v_mul_f32_e32 v48, v132, v132
	v_mul_f32_e32 v49, v134, v134
	v_mul_f32_e32 v50, v124, v124
	v_mul_f32_e32 v51, v126, v126
	v_fmac_f32_e32 v48, v133, v133
	v_fmac_f32_e32 v49, v135, v135
	v_fmac_f32_e32 v50, v125, v125
	v_fmac_f32_e32 v51, v127, v127
	v_add_f32_e32 v48, v48, v49
	v_add_f32_e32 v50, v50, v51
	v_add_f32_e32 v48, v48, v50
	v_add_f32_e32 v244, v56, v48
	ds_bpermute_b32 v245, v242, v244
	s_mov_b32 s98, 0x58000
	v_lshl_add_u64 v[240:241], v[236:237], 0, s[98:99]
	v_cvt_pk_bf16_f32 v60, v210, v211
	v_cvt_pk_bf16_f32 v61, v212, v213
	v_cvt_pk_bf16_f32 v62, v214, v215
	v_cvt_pk_bf16_f32 v63, v216, v217
	global_store_dwordx4 v[240:241], v[60:63], off
	v_cvt_pk_bf16_f32 v52, v132, v133
	v_cvt_pk_bf16_f32 v53, v134, v135
	v_cvt_pk_bf16_f32 v54, v124, v125
	v_cvt_pk_bf16_f32 v55, v126, v127
	global_store_dwordx4 v[240:241], v[52:55], off offset:256
	s_waitcnt lgkmcnt(0)
	v_add_f32_e32 v244, v244, v245
	ds_bpermute_b32 v245, v243, v244
	s_mov_b32 s98, 0x2c00
	v_lshl_add_u64 v[240:241], v[238:239], 0, s[98:99]
	s_waitcnt lgkmcnt(0)
	v_add_f32_e32 v244, v244, v245
	s_and_saveexec_b64 s[50:51], s[8:9]
	global_store_dword v[240:241], v244, off
	s_mov_b64 exec, s[50:51]
	s_branch .Lp2_epi_done
.Lp2_epi_done:
	s_andn2_b64 vcc, exec, s[10:11]
	s_mov_b64 s[10:11], -1
	s_cbranch_vccnz .LBB0_1450
	s_andn2_b64 vcc, exec, s[28:29]
	s_cbranch_vccnz .LBB0_1449
	s_barrier
	s_branch .LBB0_1449
